# work queues: each poll also reads all 8 queue counters; exhausted queues are skipped when stealing
# baseline (speedup 1.0000x reference)
; #define LAS __attribute__((address_space(3)))
; DI float wave_max(float v) { v = fmaxf(v, shx<1>(v)); v = fmaxf(v, shx<2>(v)); v = fmaxf(v, shx<4>(v)); v = fmaxf(v, shx<8>(v)); v = fmaxf(v, shx<16>(v)); v = fmaxf(v, shx<32>(v)); return v; }
; __global__ void __launch_bounds__(512, 2) mega_fwd(Args a) {
;     ...
;             unsigned* ctl = WSP(unsigned, WS_CTL); bf16_t* Qb = WSP(bf16_t, WS_Q); bf16_t* Kb = WSP(bf16_t, WS_K); bf16_t* VT = WSP(bf16_t, WS_VT); bf16_t* VTX = WSP(bf16_t, WS_VTX);
;             bf16_t* Gb = WSP(bf16_t, WS_G); bf16_t* Yb = WSP(bf16_t, WS_Y); float* FB = WSP(float, WS_F); float* KMP = WSP(float, WS_KMP);
;             float Mx[3];
; #pragma unroll
;             for (int gi = 0; gi < 3; ++gi) {
;                 const float gq = wave_max(fabsf(ap->qg[l * 192 + gi * 64 + lane])), gk = wave_max(fabsf(ap->kg[l * 192 + gi * 64 + lane]));
;                 Mx[gi] = 8.1f * gq * gk;
;             }
;             LAS float* Oacc = (LAS float*)lds; LAS float* lacc = (LAS float*)(lds + 512 * 68 * 4);
;             const int xcc = (int)(__builtin_amdgcn_s_getreg((3 << 11) | 20) & 7u);
;             const int vb = (G == 256) ? ((int)(blockIdx.x & 7) * 32 + (int)(blockIdx.x >> 3)) : (int)blockIdx.x;
;             for (int rep = 0; rep < REP_A; ++rep)
;             for (int it = vb; it < 256; it += G)
;                 attn_A_item(Qb, Kb, VT, VTX, Gb, Yb, it >> 4, it & 15, Mx[0], Oacc, lacc, tid, wave, lane);
;             for (int rep = 0; rep < REP_CD; ++rep) {
;                 LAS int* qw = (LAS int*)(lds + 147200);
;                 for (int sq = 0; sq < 8; ++sq) {
;                     const int q = (xcc + sq) & 7;
;                     unsigned* ctr = ctl + 64 * (l * 16 + q) + 1024 * 4 * rep;
.LBB0_307:
	s_movk_i32 s2, 0xff
	v_writelane_b32 v255, s2, 12
	v_readlane_b32 s2, v254, 45
	v_readlane_b32 s3, v254, 46
	s_add_u32 s71, s2, 0x24180000
	s_addc_u32 s72, s3, 0
	s_add_u32 s73, s2, 0x24200000
	v_readlane_b32 s0, v254, 42
	s_addc_u32 s74, s3, 0
	s_lshl_b32 s70, s0, 10
	v_cndmask_b32_e64 v0, v132, v133, s[6:7]
	s_add_u32 s60, s2, 0x11100000
	v_max_f32_e32 v0, v0, v0
	v_max_f32_e32 v2, v130, v130
	s_addc_u32 s61, s3, 0
	v_max_f32_e32 v0, v2, v0
	v_cndmask_b32_e64 v2, v131, v134, s[6:7]
	s_add_u32 s52, s2, 0x15100000
	v_max_f32_e32 v2, v2, v2
	v_max_f32_e32 v3, v125, v125
	s_addc_u32 s53, s3, 0
	v_max_f32_e32 v2, v3, v2
	v_mul_f32_e32 v0, 0x4101999a, v0
	s_add_u32 s76, s2, 0x19100000
	v_mul_f32_e32 v0, v0, v2
	v_cndmask_b32_e64 v2, v137, v138, s[6:7]
	s_addc_u32 s77, s3, 0
	v_max_f32_e32 v2, v2, v2
	v_max_f32_e32 v3, v135, v135
	s_add_u32 s54, s2, 0x10100000
	v_max_f32_e32 v2, v3, v2
	v_cndmask_b32_e64 v3, v139, v140, s[6:7]
	s_addc_u32 s55, s3, 0
	v_max_f32_e32 v3, v3, v3
	v_max_f32_e32 v4, v136, v136
	s_add_u32 s56, s2, 0x14100000
	v_max_f32_e32 v3, v4, v3
	v_mul_f32_e32 v2, 0x4101999a, v2
	s_addc_u32 s57, s3, 0
	v_mul_f32_e32 v180, v2, v3
	s_add_u32 s80, s2, 0x18100000
	s_mov_b32 s75, 0
	v_cmp_eq_u32_e64 s[8:9], 0, v165
	v_add_f32_e32 v182, v180, v180
	s_addc_u32 s81, s3, 0
	v_mul_f32_e32 v184, 0xbfb8aa3b, v0
	s_movk_i32 s91, 0x90
	s_mov_b32 s98, 0xff800000
	v_readlane_b32 s86, v254, 39
	v_readlane_b32 s1, v254, 43
	s_branch .LBB0_309

; __global__ void __launch_bounds__(512, 2) mega_fwd(Args a) {
;     ...
;                 for (int sq = 0; sq < 8; ++sq) {
;                     const int q = (xcc + sq) & 7;
;                     unsigned* ctr = ctl + 64 * (l * 16 + q) + 1024 * 4 * rep;
.LBB0_309:
	v_readlane_b32 s0, v254, 48
	s_add_i32 s2, s75, s0
	s_and_b32 s3, s2, 7
	v_readlane_b32 s4, v255, 12
	s_lshr_b32 s4, s4, s3
	s_and_b32 s4, s4, 1
	s_cbranch_scc0 .LBB0_308
	s_lshl_b32 s0, s3, 6
	s_or_b32 s50, s0, s70
	s_lshl_b64 s[0:1], s[50:51], 2
	v_readlane_b32 s4, v254, 45
	v_readlane_b32 s5, v254, 46
	s_add_u32 s58, s4, s0
	s_addc_u32 s59, s5, s1
	s_lshl_b32 s0, s2, 11
	s_lshl_b32 s82, s3, 1
	s_and_b32 s2, s0, 0x2000
	s_mov_b32 s3, s51
	s_branch .LBB0_312

; #define LAS __attribute__((address_space(3)))
; template <int MODE>
; DI void attn_wg2_item(const bf16_t* Qm, const bf16_t* Km, const bf16_t* Vtm, const float* Fb, const float* KMPb, const bf16_t* G, bf16_t* Y, int bh, int qb2, int halfq, int mixer, float Mb, LAS unsigned char* lds, int tid, int wave, int lane) {
;     asm volatile("" : "+v"(tid), "+v"(lane));
;     const int r = lane & 31, h = lane >> 5;
;     const int qtA = halfq ? qb2 * 8 + wave : qb2 * 16 + wave, qtB = halfq ? -1 : qb2 * 16 + 15 - wave, tA = qtA * 32 + r, tB = halfq ? tA : qtB * 32 + r;
;     bf16x8 qfA[4], qfB[4];
;     load_q(qfA, Qm + ((size_t)bh * S + tA) * 64 + 8 * h);
;     load_q(qfB, Qm + ((size_t)bh * S + tB) * 64 + 8 * h);
;     const int qblkA = qtA >> 3, qblkB = halfq ? 0 : (qtB >> 3);
;     unsigned selA = 0u, selB = 0u, visA = 0xffffffffu, visB = 0xffffffffu;
;     float fmA = 0.f, fmB = 0.f, Ft0 = 0.f;
;     if (MODE == 3) { fmA = (Fb[tA] - Mb) * LOG2E; fmB = (Fb[tB] - Mb) * LOG2E; Ft0 = Fb[halfq ? qb2 * 256 : qb2 * 512]; }
;     if (MODE == 2) {
;         selA = moba_select(KMPb, qfA, qblkA, r, h); selB = halfq ? 0u : moba_select(KMPb, qfB, qblkB, r, h);
;         visA = wave_or(selA) | (1u << qblkA); visB = wave_or(selB) | (1u << qblkB);
;     }
;     f32x16 oA0, oA1, oB0, oB1;
; #pragma unroll
;     for (int i = 0; i < 16; ++i) { oA0[i] = 0.f; oA1[i] = 0.f; oB0[i] = 0.f; oB1[i] = 0.f; }
;     float lA = 0.f, lB = 0.f;
;     const float mb2 = -Mb * LOG2E, NEGI = -__builtin_inff();
;     const int srow = tid >> 3, sch = tid & 7;
;     const bf16_t* kg = Km + ((size_t)bh * S + srow) * 64 + sch * 8;
; __global__ void __launch_bounds__(512, 2) mega_fwd(Args a) {
;     ...
;                     for (;;) {
;                         if (tid == 0) *qw = (int)atomicAdd(ctr, 1u);
;                         __syncthreads();
;                         const int idx = __builtin_amdgcn_readfirstlane(*qw);
;                         __syncthreads();
;                         if (idx >= 72) break;
;                         const int k = idx >> 2, j = idx & 3, bh = 2 * q + (j >> 1), halfq = (k >= 6 && k < 10), qb2 = k < 6 ? 13 - k : (halfq ? 37 - k : 17 - k);
;                         if (j & 1) attn_wg2_item<3>(Qb + (size_t)3 * 16 * S * 64, Kb + (size_t)3 * 16 * S * 64, VT + (size_t)3 * 16 * 64 * S, FB + (size_t)bh * S, nullptr, Gb, Yb, bh, qb2, halfq, 3, Mx[2], lds, tid, wave, lane);
.LBB0_312:
	s_and_saveexec_b64 s[0:1], s[8:9]
	s_cbranch_execz .LBB0_316
	s_mov_b64 s[10:11], exec
	v_mbcnt_lo_u32_b32 v0, s10, 0
	v_mbcnt_hi_u32_b32 v0, s11, v0
	v_cmp_eq_u32_e32 vcc, 0, v0
	s_and_saveexec_b64 s[4:5], vcc
	s_cbranch_execz .LBB0_315
	s_bcnt1_i32_b64 s10, s[10:11]
	v_mov_b32_e32 v2, s10
	global_atomic_add v2, v1, v2, s[58:59] sc0
	s_lshl_b32 s10, s82, 7
	s_sub_u32 s10, s58, s10
	s_subb_u32 s11, s59, 0
	s_mov_b64 exec, 0xff
	v_mbcnt_lo_u32_b32 v253, -1, 0
	v_lshlrev_b32_e32 v253, 8, v253
	global_load_dword v252, v253, s[10:11] sc0 sc1
	s_mov_b64 exec, 1
.LBB0_315:
	s_or_b64 exec, exec, s[4:5]
	s_waitcnt vmcnt(0)
	v_readfirstlane_b32 s4, v2
	v_mov_b32_e32 v2, s86
	s_nop 0
	v_add_u32_e32 v0, s4, v0
	ds_write_b32 v2, v0
	s_mov_b64 exec, 0xff
	v_cmp_gt_u32_e32 vcc, 0x48, v252
	s_mov_b64 exec, 1
	s_nop 1
	v_mov_b32_e32 v252, vcc_lo
	ds_write_b32 v2, v252 offset:4
.LBB0_316:
	s_or_b64 exec, exec, s[0:1]
	v_mov_b32_e32 v0, s86
	s_waitcnt lgkmcnt(0)
	s_barrier
	ds_read_b32 v252, v0 offset:4
	ds_read_b32 v0, v0
	s_mov_b64 s[0:1], -1
	s_waitcnt lgkmcnt(0)
	s_barrier
	v_readfirstlane_b32 s4, v0
	v_readfirstlane_b32 s5, v252
	s_nop 3
	v_writelane_b32 v255, s5, 12
	s_cmpk_gt_i32 s4, 0x47
	s_cbranch_scc1 .LBB0_311
	s_ashr_i32 s5, s4, 2
	s_bfe_u32 s0, s4, 0x10001
	s_or_b32 s83, s0, s82
	s_add_i32 s0, s5, -10
	s_cmp_lt_u32 s0, -4
	s_cselect_b64 s[10:11], -1, 0
	s_and_b64 s[0:1], s[10:11], exec
	s_cselect_b32 s0, 17, 37
	s_cmp_gt_i32 s5, 5
	s_cselect_b32 s0, s0, 13
	s_sub_i32 s68, s0, s5
	s_bitcmp0_b32 s4, 0
	s_cbranch_scc1 .LBB0_356
	s_lshl_b32 s50, s83, 13
	s_lshl_b32 s0, s83, 15
	s_add_u32 s0, s71, s0
	s_addc_u32 s1, s72, 0
	s_lshl_b32 s12, s68, 3
	s_lshl_b32 s13, s68, 4
	s_and_b64 s[4:5], s[10:11], exec
	v_mov_b32_e32 v7, v165
	v_mov_b32_e32 v5, v178
	s_cselect_b32 s69, s13, s12
	v_readlane_b32 s4, v254, 44
	s_add_i32 s69, s69, s4
	v_and_b32_e32 v4, 31, v5
	s_sub_i32 s4, s13, s4
	s_add_i32 s13, s4, 15
	v_lshl_or_b32 v168, s69, 5, v4
	v_ashrrev_i32_e32 v6, 5, v5
	s_and_b64 s[4:5], s[10:11], exec
	v_ashrrev_i32_e32 v169, 31, v168
	s_cselect_b32 s84, s13, -1
	v_lshl_add_u64 v[2:3], s[50:51], 0, v[168:169]
	v_lshlrev_b32_e32 v160, 3, v6
	v_lshl_or_b32 v0, s84, 5, v4
	v_lshlrev_b64 v[2:3], 7, v[2:3]
	v_ashrrev_i32_e32 v161, 31, v160
	v_cndmask_b32_e64 v166, v168, v0, s[10:11]
	v_lshl_add_u64 v[2:3], s[60:61], 0, v[2:3]
	v_lshlrev_b64 v[8:9], 1, v[160:161]
	v_lshl_add_u64 v[2:3], v[2:3], 0, v[8:9]
	v_ashrrev_i32_e32 v167, 31, v166
	global_load_dwordx4 v[96:99], v[2:3], off
	global_load_dwordx4 v[100:103], v[2:3], off offset:32
	global_load_dwordx4 v[104:107], v[2:3], off offset:64
	global_load_dwordx4 v[108:111], v[2:3], off offset:96
	v_lshl_add_u64 v[2:3], s[50:51], 0, v[166:167]
	s_cselect_b32 s4, 9, 8
	v_lshlrev_b64 v[2:3], 7, v[2:3]
	s_lshl_b32 s4, s68, s4
	s_mov_b32 s5, s51
	v_lshl_add_u64 v[2:3], s[60:61], 0, v[2:3]
	s_lshl_b64 s[4:5], s[4:5], 2
	v_lshl_add_u64 v[2:3], v[2:3], 0, v[8:9]
	s_add_u32 s4, s0, s4
	global_load_dwordx4 v[112:115], v[2:3], off
	global_load_dwordx4 v[116:119], v[2:3], off offset:32
	global_load_dwordx4 v[120:123], v[2:3], off offset:64
	global_load_dwordx4 v[124:127], v[2:3], off offset:96
	v_lshl_add_u64 v[2:3], v[168:169], 2, s[0:1]
	s_addc_u32 s5, s1, s5
	global_load_dword v8, v[2:3], off
	global_load_dword v163, v1, s[4:5]
	v_lshl_add_u64 v[2:3], v[166:167], 2, s[0:1]
	global_load_dword v9, v[2:3], off
	v_ashrrev_i32_e32 v2, 3, v7
	v_ashrrev_i32_e32 v3, 31, v2
	v_lshl_add_u64 v[10:11], s[50:51], 0, v[2:3]
	v_lshlrev_b64 v[10:11], 7, v[10:11]
	v_lshlrev_b32_e32 v186, 4, v7
	s_lshl_b32 s4, s83, 20
	v_lshl_add_u64 v[10:11], s[52:53], 0, v[10:11]
	v_and_b32_e32 v0, 0x70, v186
	s_add_u32 s4, s76, s4
	v_lshl_add_u64 v[170:171], v[10:11], 0, v[0:1]
	s_addc_u32 s5, s77, 0
	v_lshlrev_b64 v[10:11], 14, v[2:3]
	v_lshl_add_u64 v[10:11], s[4:5], 0, v[10:11]
	v_mad_u64_u32 v[174:175], s[4:5], v2, s91, v[0:1]
	s_lshl_b32 s4, s68, 2
	s_or_b32 s13, s4, 3
	s_or_b32 s12, s12, 7
	s_and_b64 s[4:5], s[10:11], exec
	s_cselect_b32 s64, s12, s13
	s_mov_b32 s65, s51
	s_lshl_b64 s[4:5], s[64:65], 13
	v_lshl_add_u64 v[172:173], v[10:11], 0, v[0:1]
	v_lshl_add_u64 v[2:3], v[170:171], 0, s[4:5]
	s_lshl_b32 s50, s64, 6
	s_lshl_b64 s[14:15], s[50:51], 2
	s_add_u32 s14, s0, s14
	s_addc_u32 s15, s1, s15
	global_load_dword v216, v1, s[14:15] offset:-4
	global_load_dwordx4 v[10:13], v[2:3], off
	v_lshl_add_u64 v[2:3], s[50:51], 1, v[172:173]
	global_load_dwordx4 v[14:17], v[2:3], off
	v_add_u32_e32 v0, 0, v174
	v_cmp_gt_i32_e64 s[12:13], 16, v7
	v_cmp_lt_i32_e32 vcc, 15, v7
	s_waitcnt vmcnt(1)
	ds_write_b128 v0, v[10:13]
	s_waitcnt vmcnt(0)
	ds_write_b128 v0, v[14:17] offset:9216
	v_lshlrev_b32_e32 v0, 2, v7
	s_and_saveexec_b64 s[4:5], vcc
	s_xor_b64 s[4:5], exec, s[4:5]
	v_lshlrev_b32_e32 v186, 4, v7
	v_mov_b64_e32 v[2:3], v[0:1]
	s_andn2_saveexec_b64 s[4:5], s[4:5]
	s_cbranch_execz .LBB0_322
	s_lshl_b64 s[14:15], s[50:51], 2
	s_add_u32 s14, s0, s14
	s_addc_u32 s15, s1, s15
	v_ashrrev_i32_e32 v3, 31, v0
	v_mov_b32_e32 v2, v0
	v_lshl_add_u64 v[10:11], v[2:3], 2, s[14:15]
	global_load_dwordx4 v[10:13], v[10:11], off
	s_mov_b32 s14, 0x3fb8aa3b
	v_add_u32_e32 v0, 0, v186
	s_waitcnt vmcnt(0)
	v_pk_mul_f32 v[12:13], v[12:13], s[14:15] op_sel_hi:[1,0]
	v_pk_mul_f32 v[10:11], v[10:11], s[14:15] op_sel_hi:[1,0]
	ds_write_b128 v0, v[10:13] offset:18432

; #define LAS __attribute__((address_space(3)))
; __global__ void __launch_bounds__(512, 2) mega_fwd(Args a) {
;     ...
;             for (int rep = 0; rep < REP_B; ++rep) {
;                 LAS int* qw = (LAS int*)(lds + 147200);
;                 for (int sq = 0; sq < 8; ++sq) {
;                     const int q = (xcc + sq) & 7;
;                     unsigned* ctr = ctl + 64 * (l * 16 + 8 + q) + 1024 * 4 * rep;
;     ...
;                         attn_wgB_item(Qb + (size_t)1 * 16 * S * 64, Kb + (size_t)1 * 16 * S * 64, VT + (size_t)1 * 16 * 64 * S, Gb, Yb, bh, qb, 1, lds, tid, wave, lane);
.LBB0_422:
	s_movk_i32 s2, 0xff
	v_writelane_b32 v255, s2, 13
	v_readlane_b32 s2, v254, 45
	v_readlane_b32 s3, v254, 46
	s_add_u32 s0, s2, 0xf100000
	s_addc_u32 s1, s3, 0
	s_add_u32 s4, s2, 0x13100000
	s_addc_u32 s5, s3, 0
	s_add_u32 s58, s2, 0x17100000
	s_addc_u32 s59, s3, 0
	v_readlane_b32 s3, v254, 44
	s_lshl_b32 s2, s3, 2
	s_add_i32 s60, s2, 0
	s_sub_i32 s61, 7, s3
	s_mov_b32 s62, 0
	v_readlane_b32 s74, v254, 35
	v_readlane_b32 s75, v254, 36
	s_mov_b32 s76, 0xffff0000
	s_mov_b32 s77, 0x800000
	s_movk_i32 s78, 0x7fff
	v_readlane_b32 s79, v254, 37
	v_readlane_b32 s80, v254, 38
	s_mov_b64 s[82:83], 0x80
	s_mov_b32 s81, 0x42d00000
	s_branch .LBB0_424

; __global__ void __launch_bounds__(512, 2) mega_fwd(Args a) {
;     ...
;                 for (int sq = 0; sq < 8; ++sq) {
;                     const int q = (xcc + sq) & 7;
;                     unsigned* ctr = ctl + 64 * (l * 16 + 8 + q) + 1024 * 4 * rep;
.LBB0_424:
	v_readlane_b32 s2, v254, 48
	s_add_i32 s10, s62, s2
	s_and_b32 s11, s10, 7
	v_readlane_b32 s2, v255, 13
	s_lshr_b32 s2, s2, s11
	s_and_b32 s2, s2, 1
	s_cbranch_scc0 .LBB0_423
	s_lshl_b32 s2, s11, 6
	s_or_b32 s50, s2, s70
	s_lshl_b64 s[2:3], s[50:51], 2
	v_readlane_b32 s12, v254, 45
	v_readlane_b32 s13, v254, 46
	s_add_u32 s48, s12, s2
	s_addc_u32 s49, s13, s3
	s_lshl_b32 s2, s10, 11
	s_lshl_b32 s63, s11, 1
	s_and_b32 s52, s2, 0x2000
	s_mov_b32 s53, s51
	s_branch .LBB0_427

; #define LAS __attribute__((address_space(3)))
; DI int kperm(int r) { return (r & ~12) | ((r & 4) << 1) | ((r & 8) >> 1); }
; DI void attn_wgB_item(const bf16_t* Qm, const bf16_t* Km, const bf16_t* Vtm, const bf16_t* G, bf16_t* Y, int bh, int qb2, int halfq, LAS unsigned char* lds, int tid, int wave, int lane) {
;     asm volatile("" : "+v"(tid), "+v"(lane));
;     const int r = lane & 31, h = lane >> 5;
;     const int qtA = halfq ? qb2 * 8 + wave : qb2 * 16 + wave, qtB = halfq ? -1 : qb2 * 16 + 15 - wave, tA = qtA * 32 + r, tB = halfq ? tA : qtB * 32 + r;
;     bf16x8 qfA[4], qfB[4];
;     load_q(qfA, Qm + ((size_t)bh * S + tA) * 64 + 8 * h);
;     load_q(qfB, Qm + ((size_t)bh * S + tB) * 64 + 8 * h);
;     f32x16 oA0, oA1, oB0, oB1;
; #pragma unroll
;     for (int i = 0; i < 16; ++i) { oA0[i] = 0.f; oA1[i] = 0.f; oB0[i] = 0.f; oB1[i] = 0.f; }
;     float RA = 0.f, RB = 0.f;
;     bool doneA = false, doneB = (halfq != 0);
;     const int srow = tid >> 3, sch = tid & 7;
;     const bf16_t* kg = Km + ((size_t)bh * S + srow) * 64 + sch * 8;
;     const bf16_t* vg = Vtm + ((size_t)bh * 64 + srow) * S + sch * 8;
;     const unsigned kws = AW_K + srow * 144 + sch * 16, vws = AW_V + srow * 144 + sch * 16;
;     const unsigned kra = AW_K + kperm(r) * 144 + 16 * h, vra = AW_V + r * 144 + 16 * h;
;     LAS int* fl = (LAS int*)(lds + 2 * AW_BUF);
;     int cur = halfq ? qb2 * 4 + 3 : qb2 * 8 + 7, buf = 0, it = 0;
;     {
;         const bf16x8 kreg = *(const bf16x8*)(kg + (size_t)cur * 4096);
;         const u32x4 vreg = *(const u32x4*)(vg + cur * 64);
;         *(LAS bf16x8*)(lds + kws) = kreg;
;         *(LAS u32x4*)(lds + vws) = vreg;
;     }
;     __syncthreads();
; __global__ void __launch_bounds__(512, 2) mega_fwd(Args a) {
;     ...
;                     for (;;) {
;                         if (tid == 0) *qw = (int)atomicAdd(ctr, 1u);
;                         __syncthreads();
;                         const int idx = __builtin_amdgcn_readfirstlane(*qw);
;                         __syncthreads();
;                         if (idx >= 64) break;
;                         const int qb = 31 - (idx >> 1), bh = 2 * q + (idx & 1);
;                         attn_wgB_item(Qb + (size_t)1 * 16 * S * 64, Kb + (size_t)1 * 16 * S * 64, VT + (size_t)1 * 16 * 64 * S, Gb, Yb, bh, qb, 1, lds, tid, wave, lane);
.LBB0_427:
	s_and_saveexec_b64 s[2:3], s[8:9]
	s_cbranch_execz .LBB0_431
	s_mov_b64 s[12:13], exec
	v_mbcnt_lo_u32_b32 v0, s12, 0
	v_mbcnt_hi_u32_b32 v0, s13, v0
	v_cmp_eq_u32_e32 vcc, 0, v0
	s_and_saveexec_b64 s[10:11], vcc
	s_cbranch_execz .LBB0_430
	s_bcnt1_i32_b64 s12, s[12:13]
	v_mov_b32_e32 v2, s12
	global_atomic_add v2, v1, v2, s[48:49] offset:2048 sc0
	s_lshl_b32 s12, s63, 7
	s_sub_u32 s12, s48, s12
	s_subb_u32 s13, s49, 0
	s_mov_b64 exec, 0xff
	v_mbcnt_lo_u32_b32 v253, -1, 0
	v_lshlrev_b32_e32 v253, 8, v253
	global_load_dword v252, v253, s[12:13] offset:2048 sc0 sc1
	s_mov_b64 exec, 1
.LBB0_430:
	s_or_b64 exec, exec, s[10:11]
	s_waitcnt vmcnt(0)
	v_readfirstlane_b32 s10, v2
	v_mov_b32_e32 v2, s86
	s_nop 0
	v_add_u32_e32 v0, s10, v0
	ds_write_b32 v2, v0
	s_mov_b64 exec, 0xff
	v_cmp_gt_u32_e32 vcc, 64, v252
	s_mov_b64 exec, 1
	s_nop 1
	v_mov_b32_e32 v252, vcc_lo
	ds_write_b32 v2, v252 offset:4
.LBB0_431:
	s_or_b64 exec, exec, s[2:3]
	v_mov_b32_e32 v0, s86
	s_waitcnt lgkmcnt(0)
	s_barrier
	ds_read_b32 v252, v0 offset:4
	ds_read_b32 v0, v0
	s_mov_b64 s[2:3], -1
	s_waitcnt lgkmcnt(0)
	s_barrier
	v_readfirstlane_b32 s10, v0
	v_readfirstlane_b32 s11, v252
	s_nop 3
	v_writelane_b32 v255, s11, 13
	s_cmp_gt_i32 s10, 63
	s_cbranch_scc1 .LBB0_426
	s_and_b32 s2, s10, 1
	v_mov_b32_e32 v0, v165
	v_mov_b32_e32 v14, v178
	s_ashr_i32 s54, s10, 1
	s_or_b32 s64, s2, s63
	s_sub_i32 s11, 31, s54
	v_ashrrev_i32_e32 v12, 3, v0
	s_lshl_b32 s50, s64, 13
	v_ashrrev_i32_e32 v13, 31, v12
	s_lshl_b32 s65, s11, 3
	v_readlane_b32 s2, v254, 44
	v_lshl_add_u64 v[2:3], s[50:51], 0, v[12:13]
	v_and_b32_e32 v15, 31, v14
	s_add_i32 s65, s65, s2
	v_lshlrev_b64 v[2:3], 7, v[2:3]
	v_lshlrev_b32_e32 v0, 4, v0
	s_lshl_b32 s2, s64, 20
	v_lshl_or_b32 v108, s65, 5, v15
	v_lshl_add_u64 v[2:3], s[4:5], 0, v[2:3]
	v_and_b32_e32 v0, 0x70, v0
	s_add_u32 s2, s58, s2
	v_ashrrev_i32_e32 v109, 31, v108
	v_lshl_add_u64 v[110:111], v[2:3], 0, v[0:1]
	s_addc_u32 s3, s59, 0
	v_lshlrev_b64 v[2:3], 14, v[12:13]
	v_lshl_add_u64 v[10:11], s[50:51], 0, v[108:109]
	v_lshl_add_u64 v[2:3], s[2:3], 0, v[2:3]
	s_lshl_b32 s2, s11, 2
	v_ashrrev_i32_e32 v13, 5, v14
	s_or_b32 s50, s2, 3
	v_lshlrev_b32_e32 v106, 3, v13
	v_lshlrev_b64 v[10:11], 7, v[10:11]
	v_lshl_add_u64 v[112:113], v[2:3], 0, v[0:1]
	s_lshl_b64 s[2:3], s[50:51], 13
	s_lshl_b32 s50, s50, 6
	v_ashrrev_i32_e32 v107, 31, v106
	v_lshl_add_u64 v[10:11], s[0:1], 0, v[10:11]
	v_lshl_add_u64 v[2:3], v[110:111], 0, s[2:3]
	v_lshl_add_u64 v[6:7], s[50:51], 1, v[112:113]
	v_lshl_add_u64 v[10:11], v[106:107], 1, v[10:11]
	global_load_dwordx4 v[2:5], v[2:3], off
	s_nop 0
	global_load_dwordx4 v[6:9], v[6:7], off
	s_nop 0
	global_load_dwordx4 v[64:67], v[10:11], off
	global_load_dwordx4 v[68:71], v[10:11], off offset:32
	global_load_dwordx4 v[72:75], v[10:11], off offset:64
	global_load_dwordx4 v[76:79], v[10:11], off offset:96
	v_lshlrev_b32_e32 v11, 1, v14
	v_lshrrev_b32_e32 v16, 1, v14
	v_mul_lo_u32 v12, v12, s91
	v_and_b32_e32 v10, 19, v14
	v_and_b32_e32 v11, 8, v11
	v_and_b32_e32 v16, 4, v16
	v_add3_u32 v117, v12, v0, 0
	v_or_b32_e32 v0, 1, v106
	v_lshlrev_b32_e32 v105, 4, v13
	v_or3_b32 v10, v10, v11, v16
	v_or_b32_e32 v11, 2, v106
	v_or_b32_e32 v12, 3, v106
	v_or_b32_e32 v13, 4, v106
	v_or_b32_e32 v16, 5, v106
	v_or_b32_e32 v17, 6, v106
	v_or_b32_e32 v18, 7, v106
	v_add_u32_e32 v104, 16, v106
	v_add_u32_e32 v19, 17, v106
	v_add_u32_e32 v20, 18, v106
	v_add_u32_e32 v21, 19, v106
	v_add_u32_e32 v22, 20, v106
	v_add_u32_e32 v23, 21, v106
	v_add_u32_e32 v24, 22, v106
	v_cmp_lt_i32_e64 s[12:13], v0, v15
	v_add_u32_e32 v0, 23, v106
	s_lshl_b32 s2, s54, 2
	v_mul_u32_u24_e32 v116, 0x90, v15
	v_cmp_lt_i32_e64 s[10:11], v106, v15
	v_cmp_lt_i32_e64 s[14:15], v11, v15
	v_cmp_lt_i32_e64 s[16:17], v12, v15
	v_cmp_lt_i32_e64 s[18:19], v13, v15
	v_cmp_lt_i32_e64 s[20:21], v16, v15
	v_cmp_lt_i32_e64 s[22:23], v17, v15
	v_cmp_lt_i32_e64 s[24:25], v18, v15
	v_cmp_lt_i32_e64 s[26:27], v104, v15
	v_cmp_lt_i32_e64 s[28:29], v19, v15
	v_cmp_lt_i32_e64 s[30:31], v20, v15
	v_cmp_lt_i32_e64 s[34:35], v21, v15
	v_cmp_lt_i32_e64 s[36:37], v22, v15
	v_cmp_lt_i32_e64 s[38:39], v23, v15
	v_cmp_lt_i32_e64 s[40:41], v24, v15
	v_cmp_lt_i32_e64 s[42:43], v0, v15
	v_cmp_gt_u32_e64 s[44:45], 32, v14
	v_cmp_eq_u32_e64 s[46:47], 0, v14
	s_sub_i32 s50, 0x7e, s2
	s_lshl_b32 s2, s54, 3
	v_mov_b32_e32 v14, v1
	v_mov_b32_e32 v15, v1
	v_mul_u32_u24_e32 v118, 0x90, v10
	s_waitcnt vmcnt(5)
	ds_write_b128 v117, v[2:5]
	s_waitcnt vmcnt(4)
	ds_write_b128 v117, v[6:9] offset:9216
	s_sub_i32 s67, 0xfe, s2
	s_lshl_b32 s2, s54, 8
	v_mov_b32_e32 v0, v1
	v_mov_b32_e32 v2, v1
	v_mov_b32_e32 v3, v1
	v_mov_b32_e32 v4, v1
	v_mov_b32_e32 v5, v1
	v_mov_b32_e32 v6, v1
	v_mov_b32_e32 v7, v1
	v_mov_b32_e32 v8, v1
	v_mov_b32_e32 v9, v1
	v_mov_b32_e32 v10, v1
	v_mov_b32_e32 v11, v1
	v_mov_b32_e32 v12, v1
	v_mov_b32_e32 v13, v1
	v_mov_b64_e32 v[30:31], v[14:15]
	v_mov_b64_e32 v[46:47], v[14:15]
	s_mov_b32 s66, 0
	s_sub_i32 s2, 0x1f80, s2
	v_mov_b32_e32 v119, 0
	s_mov_b64 s[56:57], 0
	s_mov_b32 s68, s61
	s_mov_b32 s69, 0
	v_mov_b64_e32 v[28:29], v[12:13]
	v_mov_b64_e32 v[26:27], v[10:11]
	v_mov_b64_e32 v[24:25], v[8:9]
	v_mov_b64_e32 v[22:23], v[6:7]
	v_mov_b64_e32 v[20:21], v[4:5]
	v_mov_b64_e32 v[18:19], v[2:3]
	v_mov_b64_e32 v[16:17], v[0:1]
	v_mov_b64_e32 v[44:45], v[12:13]
	v_mov_b64_e32 v[42:43], v[10:11]
	v_mov_b64_e32 v[40:41], v[8:9]
	v_mov_b64_e32 v[38:39], v[6:7]
	v_mov_b64_e32 v[36:37], v[4:5]
	v_mov_b64_e32 v[34:35], v[2:3]
	v_mov_b64_e32 v[32:33], v[0:1]
	s_waitcnt vmcnt(0) lgkmcnt(0)
	s_barrier
	s_branch .LBB0_434
